# mLSTM h finalize: den row broadcast by DPP row_newbcast instead of ds_bpermute (two fewer LDS round trips in the serial section), on top of prefetch-after-barrier, latch waits, counted lgkmcnt, select
# speedup vs baseline: 1.0225x; 1.0004x over previous
; #define LAS __attribute__((address_space(3)))
; DEV void mlstm_b_wave(LAS char* shm, const bf16x8 (&qfr)[8], int fr, int fq, f32x4 (&nacc)[3]) {
;     constexpr int CB = 81408, RS = 528;
;     const LAS char* cbp = shm + CB + fr * RS + fq * 16;
;     bf16x8 cf[3];
; #pragma unroll
;     for (int vt = 0; vt < 3; ++vt) cf[vt] = *(const LAS bf16x8*)(cbp + vt * 16 * RS);
; #pragma unroll
;     for (int ks = 0; ks < 8; ++ks) {
;         bf16x8 cn[3] = {cf[0], cf[1], cf[2]};
;         if (ks < 7) {
; #pragma unroll
;             for (int vt = 0; vt < 3; ++vt) cn[vt] = *(const LAS bf16x8*)(cbp + vt * 16 * RS + (ks + 1) * 64);
;         }
; #pragma unroll
;         for (int vt = 0; vt < 3; ++vt) nacc[vt] = __builtin_amdgcn_mfma_f32_16x16x32_bf16(qfr[ks], cf[vt], nacc[vt], 0, 0, 0);
; #pragma unroll
;         for (int vt = 0; vt < 3; ++vt) cf[vt] = cn[vt];
;     }
; }
; template <int SKIP>
; DEV void mlstm_phase(LAS char* shm, const bf16_t* q, const bf16_t* k, const bf16_t* v, const float* gpart, const float* b_ig, const float* b_fg, bf16_t* hc, const bool pre) {
;     ...
;                 mlstm_b_wave(shm, qfr, fr, fq, nacc);
;                 const f32x4 pm4 = *(const LAS f32x4*)(tp + j * 64 + 16 * tt + 4 * fq);
; #pragma unroll
;                 for (int vt = 0; vt < 3; ++vt)
; #pragma unroll
;                     for (int r = 0; r < 4; ++r) part[(16 * tt + 4 * fq + r) * PRS + 16 * vt + fr] = __expf(m_prev - fmaxf(m_prev, pm4[r])) * nacc[vt][r];
.Lpf0_skip:
.Lpf0_done:
	v_add_u32_e32 v2, s40, v204
	s_mov_b64 s[0:1], -1
	s_and_b64 vcc, exec, s[84:85]
	v_add_u32_e32 v228, 0x23500, v2
	s_cbranch_vccz .LBB0_652
	ds_read_b128 v[110:113], v209
	ds_read_b128 v[114:117], v209 offset:8448
	ds_read_b128 v[118:121], v209 offset:16896
	ds_read_b128 v[122:125], v209 offset:64
	ds_read_b128 v[126:129], v209 offset:8512
	ds_read_b128 v[130:133], v209 offset:16960
	s_waitcnt lgkmcnt(3)
	v_mfma_f32_16x16x32_bf16 v[110:113], v[38:41], v[110:113], 0
	ds_read_b128 v[134:137], v209 offset:128
	ds_read_b128 v[138:141], v209 offset:8576
	ds_read_b128 v[142:145], v209 offset:17024
	s_mov_b64 s[0:1], 0
	v_mfma_f32_16x16x32_bf16 v[114:117], v[38:41], v[114:117], 0
	v_mfma_f32_16x16x32_bf16 v[118:121], v[38:41], v[118:121], 0
	s_waitcnt lgkmcnt(3)
	v_mfma_f32_16x16x32_bf16 v[110:113], v[34:37], v[122:125], v[110:113]
	v_mfma_f32_16x16x32_bf16 v[114:117], v[34:37], v[126:129], v[114:117]
	v_mfma_f32_16x16x32_bf16 v[118:121], v[34:37], v[130:133], v[118:121]
	ds_read_b128 v[122:125], v209 offset:192
	ds_read_b128 v[126:129], v209 offset:8640
	ds_read_b128 v[130:133], v209 offset:17088
	s_waitcnt lgkmcnt(3)
	v_mfma_f32_16x16x32_bf16 v[110:113], v[30:33], v[134:137], v[110:113]
	v_mfma_f32_16x16x32_bf16 v[114:117], v[30:33], v[138:141], v[114:117]
	v_mfma_f32_16x16x32_bf16 v[118:121], v[30:33], v[142:145], v[118:121]
	ds_read_b128 v[134:137], v209 offset:256
	ds_read_b128 v[138:141], v209 offset:8704
	ds_read_b128 v[142:145], v209 offset:17152
	s_waitcnt lgkmcnt(3)
	v_mfma_f32_16x16x32_bf16 v[110:113], v[10:13], v[122:125], v[110:113]
	v_mfma_f32_16x16x32_bf16 v[114:117], v[10:13], v[126:129], v[114:117]
	v_mfma_f32_16x16x32_bf16 v[118:121], v[10:13], v[130:133], v[118:121]
	ds_read_b128 v[122:125], v209 offset:320
	ds_read_b128 v[126:129], v209 offset:8768
	ds_read_b128 v[130:133], v209 offset:17216
	s_waitcnt lgkmcnt(3)
	v_mfma_f32_16x16x32_bf16 v[110:113], v[26:29], v[134:137], v[110:113]
	v_mfma_f32_16x16x32_bf16 v[114:117], v[26:29], v[138:141], v[114:117]
	v_mfma_f32_16x16x32_bf16 v[118:121], v[26:29], v[142:145], v[118:121]
	ds_read_b128 v[134:137], v209 offset:384
	ds_read_b128 v[138:141], v209 offset:8832
	ds_read_b128 v[142:145], v209 offset:17280
	s_waitcnt lgkmcnt(3)
	v_mfma_f32_16x16x32_bf16 v[110:113], v[22:25], v[122:125], v[110:113]
	v_mfma_f32_16x16x32_bf16 v[114:117], v[22:25], v[126:129], v[114:117]
	v_mfma_f32_16x16x32_bf16 v[118:121], v[22:25], v[130:133], v[118:121]
	ds_read_b128 v[122:125], v209 offset:17344
	ds_read_b128 v[126:129], v209 offset:448
	ds_read_b128 v[130:133], v209 offset:8896
	s_waitcnt lgkmcnt(0)
	v_mfma_f32_16x16x32_bf16 v[110:113], v[14:17], v[134:137], v[110:113]
	v_mfma_f32_16x16x32_bf16 v[134:137], v[14:17], v[142:145], v[118:121]
	v_mfma_f32_16x16x32_bf16 v[118:121], v[18:21], v[126:129], v[110:113]
	s_nop 5
	ds_read_b128 v[110:113], v228
	v_mfma_f32_16x16x32_bf16 v[114:117], v[14:17], v[138:141], v[114:117]
	s_waitcnt lgkmcnt(0)
	v_max_f32_e32 v0, v110, v110
	v_max_f32_e32 v4, v111, v111
	v_max_f32_e32 v0, v227, v0
	v_max_f32_e32 v4, v227, v4
	v_sub_f32_e32 v0, s28, v0
	v_sub_f32_e32 v4, s28, v4
	v_max_f32_e32 v110, v112, v112
	v_max_f32_e32 v112, v113, v113
	v_mul_f32_e32 v0, 0x3fb8aa3b, v0
	v_mul_f32_e32 v4, 0x3fb8aa3b, v4
	v_max_f32_e32 v110, v227, v110
	v_max_f32_e32 v112, v227, v112
	v_mfma_f32_16x16x32_bf16 v[114:117], v[18:21], v[130:133], v[114:117]
	v_exp_f32_e32 v0, v0
	v_exp_f32_e32 v4, v4
	v_sub_f32_e32 v110, s28, v110
	v_mfma_f32_16x16x32_bf16 v[122:125], v[18:21], v[122:125], v[134:137]
	v_sub_f32_e32 v112, s28, v112
	v_mul_f32_e32 v110, 0x3fb8aa3b, v110
	v_mul_f32_e32 v112, 0x3fb8aa3b, v112
	v_exp_f32_e32 v110, v110
	v_exp_f32_e32 v112, v112
	v_mul_f32_e32 v1, v118, v0
	v_mul_f32_e32 v5, v119, v4
	v_mul_f32_e32 v126, v114, v0
	v_mul_f32_e32 v0, v122, v0
	ds_write2_b32 v219, v1, v126 offset1:16
	v_mul_f32_e32 v1, v115, v4
	ds_write2_b32 v219, v0, v5 offset0:32 offset1:52
	v_mul_f32_e32 v0, v123, v4
	v_mul_f32_e32 v111, v120, v110
	v_mul_f32_e32 v113, v121, v112
	v_mul_f32_e32 v126, v116, v110
	ds_write2_b32 v219, v1, v0 offset0:68 offset1:84
	v_mul_f32_e32 v0, v124, v110
	ds_write2_b32 v219, v111, v126 offset0:104 offset1:120
	v_mul_f32_e32 v111, v117, v112
	ds_write2_b32 v219, v0, v113 offset0:136 offset1:156
	v_mul_f32_e32 v0, v125, v112
	ds_write2_b32 v219, v111, v0 offset0:172 offset1:188

; #define LAS __attribute__((address_space(3)))
; template <int SKIP>
; DEV void mlstm_phase(LAS char* shm, const bf16_t* q, const bf16_t* k, const bf16_t* v, const float* gpart, const float* b_ig, const float* b_fg, bf16_t* hc, const bool pre) {
;     ...
;             if (wid < 4 && !(SKIP & 16)) {
;                 const f32x4 pm4 = *(const LAS f32x4*)(tp + j * 64 + 16 * tt + 4 * fq);
;                 const f32x4 bc4 = *(const LAS f32x4*)(tb + j * 64 + 16 * tt + 4 * fq);
; #pragma unroll
;                 for (int vt = 0; vt < 3; ++vt)
; #pragma unroll
;                     for (int r = 0; r < 4; ++r) nacc[vt][r] += part[(16 * tt + 4 * fq + r) * PRS + 16 * vt + fr];
; #pragma unroll
;                 for (int r = 0; r < 4; ++r) {
;                     const float den = __shfl(nacc[2][r], lane & 48);
;                     const float inv = __builtin_amdgcn_rcpf(fmaxf(fabsf(den), __expf(-(bc4[r] + fmaxf(m_prev, pm4[r])))));
;                     LAS bf16_t* hrow = (LAS bf16_t*)(shm + HST + (16 * tt + 4 * fq + r) * 80);
;                     hrow[fr] = f2bf(nacc[0][r] * inv);
;                     hrow[16 + fr] = f2bf(nacc[1][r] * inv);
;                 }
;                 asm volatile("s_waitcnt lgkmcnt(0)" ::: "memory");
;                 {
;                     const int rw = 16 * tt + (lane >> 2), pc = lane & 3;
;                     const u32x4 hv = *(const LAS u32x4*)(shm + HST + rw * 80 + pc * 16);
;                     *(uint4*)(hc + cb + (size_t)rw * DM + vs * 32 + pc * 8) = make_uint4(hv[0], hv[1], hv[2], hv[3]);
;                 }
.LBB0_668:
	s_waitcnt lgkmcnt(0)
	s_barrier
	s_and_b64 vcc, exec, s[26:27]
	s_cbranch_vccnz .LBB0_670
	ds_read_b128 v[10:13], v228
	ds_read2_b32 v[0:1], v219 offset1:16
	ds_read2_b32 v[4:5], v211 offset1:16
	ds_read2_b32 v[18:19], v211 offset0:32 offset1:52
	ds_read2_b32 v[20:21], v211 offset0:104 offset1:120
	ds_read_b32 v24, v219 offset:128
	v_add_u32_e32 v2, 0x1f500, v2
	s_waitcnt lgkmcnt(4)
	v_add_f32_e32 v22, v118, v0
	v_add_f32_e32 v23, v114, v1
	ds_read2_b32 v[0:1], v211 offset0:68 offset1:84
	ds_read_b128 v[14:17], v2
	ds_read_b32 v2, v211 offset:544
	v_and_or_b32 v25, v214, 64, v179
	v_max_f32_e32 v10, v10, v10
	s_waitcnt lgkmcnt(3)
	v_add_f32_e32 v24, v122, v24
	v_lshlrev_b32_e32 v25, 2, v25
	v_max_f32_e32 v10, v227, v10
	v_mov_b32_dpp v24, v24 row_newbcast:0 row_mask:0xf bank_mask:0xf
	s_waitcnt lgkmcnt(1)
	v_add_f32_e32 v10, v14, v10
	v_mul_f32_e32 v10, 0xbfb8aa3b, v10
	v_exp_f32_e32 v10, v10
	v_add_f32_e32 v14, v117, v21
	s_waitcnt lgkmcnt(0)
	v_max_f32_e64 v21, |v24|, |v24|
	v_max_f32_e32 v11, v11, v11
	v_max_f32_e32 v10, v21, v10
	v_rcp_f32_e32 v10, v10
	v_add_f32_e32 v18, v123, v18
	v_max_f32_e32 v11, v227, v11
	s_nop 0
	v_mov_b32_dpp v18, v18 row_newbcast:0 row_mask:0xf bank_mask:0xf
	v_add_f32_e32 v11, v15, v11
	v_mul_f32_e32 v11, 0xbfb8aa3b, v11
	v_exp_f32_e32 v11, v11
	v_mul_f32_e32 v21, v22, v10
	v_cvt_pk_bf16_f32 v15, v21, s0
	ds_write_b16 v212, v15
	s_waitcnt lgkmcnt(1)
	v_max_f32_e64 v15, |v18|, |v18|
	v_max_f32_e32 v11, v15, v11
	v_rcp_f32_e32 v11, v11
	v_mul_f32_e32 v10, v23, v10
	v_add_f32_e32 v4, v119, v4
	v_cvt_pk_bf16_f32 v10, v10, s0
	ds_write_b16 v212, v10 offset:32
	v_mul_f32_e32 v4, v4, v11
	v_max_f32_e32 v10, v12, v12
	v_add_f32_e32 v5, v115, v5
	v_add_f32_e32 v1, v124, v1
	v_max_f32_e32 v10, v227, v10
	v_cvt_pk_bf16_f32 v4, v4, s0
	v_mov_b32_dpp v1, v1 row_newbcast:0 row_mask:0xf bank_mask:0xf
	v_add_f32_e32 v10, v16, v10
	ds_write_b16 v212, v4 offset:80
	v_mul_f32_e32 v4, v5, v11
	v_max_f32_e32 v5, v13, v13
	v_add_f32_e32 v2, v125, v2
	v_mul_f32_e32 v10, 0xbfb8aa3b, v10
	v_max_f32_e32 v5, v227, v5
	v_exp_f32_e32 v10, v10
	v_mov_b32_dpp v2, v2 row_newbcast:0 row_mask:0xf bank_mask:0xf
	v_add_f32_e32 v5, v17, v5
	v_mul_f32_e32 v5, 0xbfb8aa3b, v5
	v_exp_f32_e32 v5, v5
	s_nop 0
	v_max_f32_e64 v1, |v1|, |v1|
	v_max_f32_e32 v1, v1, v10
	v_rcp_f32_e32 v1, v1
	s_nop 0
	v_max_f32_e64 v2, |v2|, |v2|
	v_max_f32_e32 v2, v2, v5
	v_rcp_f32_e32 v2, v2
	v_add_f32_e32 v0, v116, v0
	v_mul_f32_e32 v0, v0, v1
	v_add_f32_e32 v20, v121, v20
	v_cvt_pk_bf16_f32 v0, v0, s0
	ds_write_b16 v212, v0 offset:192
	v_mul_f32_e32 v0, v20, v2
	v_add_f32_e32 v19, v120, v19
	v_cvt_pk_bf16_f32 v4, v4, s0
	v_cvt_pk_bf16_f32 v0, v0, s0
	ds_write_b16 v212, v4 offset:112
	v_mul_f32_e32 v4, v19, v1
	ds_write_b16 v212, v0 offset:240
	v_mul_f32_e32 v0, v14, v2
	v_cvt_pk_bf16_f32 v4, v4, s0
	v_cvt_pk_bf16_f32 v0, v0, s0
	ds_write_b16 v212, v4 offset:160
	ds_write_b16 v212, v0 offset:272
	s_waitcnt lgkmcnt(0)
	ds_read_b128 v[10:13], v213
	v_lshl_add_u64 v[0:1], v[172:173], 0, s[74:75]
	v_add_co_u32_e32 v0, vcc, 0x4024000, v0
	s_nop 1
	v_addc_co_u32_e32 v1, vcc, 0, v1, vcc
	s_waitcnt lgkmcnt(0)
	global_store_dwordx4 v[0:1], v[10:13], off

; #define LAS __attribute__((address_space(3)))
; DEV void mlstm_b_wave(LAS char* shm, const bf16x8 (&qfr)[8], int fr, int fq, f32x4 (&nacc)[3]) {
;     constexpr int CB = 81408, RS = 528;
;     const LAS char* cbp = shm + CB + fr * RS + fq * 16;
;     bf16x8 cf[3];
; #pragma unroll
;     for (int vt = 0; vt < 3; ++vt) cf[vt] = *(const LAS bf16x8*)(cbp + vt * 16 * RS);
; #pragma unroll
;     for (int ks = 0; ks < 8; ++ks) {
;         bf16x8 cn[3] = {cf[0], cf[1], cf[2]};
;         if (ks < 7) {
; #pragma unroll
;             for (int vt = 0; vt < 3; ++vt) cn[vt] = *(const LAS bf16x8*)(cbp + vt * 16 * RS + (ks + 1) * 64);
;         }
; #pragma unroll
;         for (int vt = 0; vt < 3; ++vt) nacc[vt] = __builtin_amdgcn_mfma_f32_16x16x32_bf16(qfr[ks], cf[vt], nacc[vt], 0, 0, 0);
; #pragma unroll
;         for (int vt = 0; vt < 3; ++vt) cf[vt] = cn[vt];
;     }
; }
; template <int SKIP>
; DEV void mlstm_phase(LAS char* shm, const bf16_t* q, const bf16_t* k, const bf16_t* v, const float* gpart, const float* b_ig, const float* b_fg, bf16_t* hc, const bool pre) {
;     ...
;                 mlstm_b_wave(shm, qfr, fr, fq, nacc);
;                 const f32x4 pm4 = *(const LAS f32x4*)(tp + j * 64 + 16 * tt + 4 * fq);
; #pragma unroll
;                 for (int vt = 0; vt < 3; ++vt)
; #pragma unroll
;                     for (int r = 0; r < 4; ++r) part[(16 * tt + 4 * fq + r) * PRS + 16 * vt + fr] = __expf(m_prev - fmaxf(m_prev, pm4[r])) * nacc[vt][r];
.Lpf1_skip:
.Lpf1_done:
	v_add_u32_e32 v2, s40, v204
	s_mov_b64 s[0:1], -1
	s_and_b64 vcc, exec, s[70:71]
	v_add_u32_e32 v228, 0x23500, v2
	s_cbranch_vccz .LBB0_1503
	ds_read_b128 v[110:113], v209
	ds_read_b128 v[114:117], v209 offset:8448
	ds_read_b128 v[118:121], v209 offset:16896
	ds_read_b128 v[122:125], v209 offset:64
	ds_read_b128 v[126:129], v209 offset:8512
	ds_read_b128 v[130:133], v209 offset:16960
	s_waitcnt lgkmcnt(3)
	v_mfma_f32_16x16x32_bf16 v[110:113], v[38:41], v[110:113], 0
	ds_read_b128 v[134:137], v209 offset:128
	ds_read_b128 v[138:141], v209 offset:8576
	ds_read_b128 v[142:145], v209 offset:17024
	s_mov_b64 s[0:1], 0
	v_mfma_f32_16x16x32_bf16 v[114:117], v[38:41], v[114:117], 0
	v_mfma_f32_16x16x32_bf16 v[118:121], v[38:41], v[118:121], 0
	s_waitcnt lgkmcnt(3)
	v_mfma_f32_16x16x32_bf16 v[110:113], v[34:37], v[122:125], v[110:113]
	v_mfma_f32_16x16x32_bf16 v[114:117], v[34:37], v[126:129], v[114:117]
	v_mfma_f32_16x16x32_bf16 v[118:121], v[34:37], v[130:133], v[118:121]
	ds_read_b128 v[122:125], v209 offset:192
	ds_read_b128 v[126:129], v209 offset:8640
	ds_read_b128 v[130:133], v209 offset:17088
	s_waitcnt lgkmcnt(3)
	v_mfma_f32_16x16x32_bf16 v[110:113], v[30:33], v[134:137], v[110:113]
	v_mfma_f32_16x16x32_bf16 v[114:117], v[30:33], v[138:141], v[114:117]
	v_mfma_f32_16x16x32_bf16 v[118:121], v[30:33], v[142:145], v[118:121]
	ds_read_b128 v[134:137], v209 offset:256
	ds_read_b128 v[138:141], v209 offset:8704
	ds_read_b128 v[142:145], v209 offset:17152
	s_waitcnt lgkmcnt(3)
	v_mfma_f32_16x16x32_bf16 v[110:113], v[10:13], v[122:125], v[110:113]
	v_mfma_f32_16x16x32_bf16 v[114:117], v[10:13], v[126:129], v[114:117]
	v_mfma_f32_16x16x32_bf16 v[118:121], v[10:13], v[130:133], v[118:121]
	ds_read_b128 v[122:125], v209 offset:320
	ds_read_b128 v[126:129], v209 offset:8768
	ds_read_b128 v[130:133], v209 offset:17216
	s_waitcnt lgkmcnt(3)
	v_mfma_f32_16x16x32_bf16 v[110:113], v[26:29], v[134:137], v[110:113]
	v_mfma_f32_16x16x32_bf16 v[114:117], v[26:29], v[138:141], v[114:117]
	v_mfma_f32_16x16x32_bf16 v[118:121], v[26:29], v[142:145], v[118:121]
	ds_read_b128 v[134:137], v209 offset:384
	ds_read_b128 v[138:141], v209 offset:8832
	ds_read_b128 v[142:145], v209 offset:17280
	s_waitcnt lgkmcnt(3)
	v_mfma_f32_16x16x32_bf16 v[110:113], v[22:25], v[122:125], v[110:113]
	v_mfma_f32_16x16x32_bf16 v[114:117], v[22:25], v[126:129], v[114:117]
	v_mfma_f32_16x16x32_bf16 v[118:121], v[22:25], v[130:133], v[118:121]
	ds_read_b128 v[122:125], v209 offset:17344
	ds_read_b128 v[126:129], v209 offset:448
	ds_read_b128 v[130:133], v209 offset:8896
	s_waitcnt lgkmcnt(0)
	v_mfma_f32_16x16x32_bf16 v[110:113], v[14:17], v[134:137], v[110:113]
	v_mfma_f32_16x16x32_bf16 v[134:137], v[14:17], v[142:145], v[118:121]
	v_mfma_f32_16x16x32_bf16 v[118:121], v[18:21], v[126:129], v[110:113]
	s_nop 5
	ds_read_b128 v[110:113], v228
	v_mfma_f32_16x16x32_bf16 v[114:117], v[14:17], v[138:141], v[114:117]
	s_waitcnt lgkmcnt(0)
	v_max_f32_e32 v0, v110, v110
	v_max_f32_e32 v4, v111, v111
	v_max_f32_e32 v0, v227, v0
	v_max_f32_e32 v4, v227, v4
	v_sub_f32_e32 v0, s28, v0
	v_sub_f32_e32 v4, s28, v4
	v_max_f32_e32 v110, v112, v112
	v_max_f32_e32 v112, v113, v113
	v_mul_f32_e32 v0, 0x3fb8aa3b, v0
	v_mul_f32_e32 v4, 0x3fb8aa3b, v4
	v_max_f32_e32 v110, v227, v110
	v_max_f32_e32 v112, v227, v112
	v_mfma_f32_16x16x32_bf16 v[114:117], v[18:21], v[130:133], v[114:117]
	v_exp_f32_e32 v0, v0
	v_exp_f32_e32 v4, v4
	v_sub_f32_e32 v110, s28, v110
	v_mfma_f32_16x16x32_bf16 v[122:125], v[18:21], v[122:125], v[134:137]
	v_sub_f32_e32 v112, s28, v112
	v_mul_f32_e32 v110, 0x3fb8aa3b, v110
	v_mul_f32_e32 v112, 0x3fb8aa3b, v112
	v_exp_f32_e32 v110, v110
	v_exp_f32_e32 v112, v112
	v_mul_f32_e32 v1, v118, v0
	v_mul_f32_e32 v5, v119, v4
	v_mul_f32_e32 v126, v114, v0
	v_mul_f32_e32 v0, v122, v0
	ds_write2_b32 v219, v1, v126 offset1:16
	v_mul_f32_e32 v1, v115, v4
	ds_write2_b32 v219, v0, v5 offset0:32 offset1:52
	v_mul_f32_e32 v0, v123, v4
	v_mul_f32_e32 v111, v120, v110
	v_mul_f32_e32 v113, v121, v112
	v_mul_f32_e32 v126, v116, v110
	ds_write2_b32 v219, v1, v0 offset0:68 offset1:84
	v_mul_f32_e32 v0, v124, v110
	ds_write2_b32 v219, v111, v126 offset0:104 offset1:120
	v_mul_f32_e32 v111, v117, v112
	ds_write2_b32 v219, v0, v113 offset0:136 offset1:156
	v_mul_f32_e32 v0, v125, v112
	ds_write2_b32 v219, v111, v0 offset0:172 offset1:188

; #define LAS __attribute__((address_space(3)))
; template <int SKIP>
; DEV void mlstm_phase(LAS char* shm, const bf16_t* q, const bf16_t* k, const bf16_t* v, const float* gpart, const float* b_ig, const float* b_fg, bf16_t* hc, const bool pre) {
;     ...
;             if (wid < 4 && !(SKIP & 16)) {
;                 const f32x4 pm4 = *(const LAS f32x4*)(tp + j * 64 + 16 * tt + 4 * fq);
;                 const f32x4 bc4 = *(const LAS f32x4*)(tb + j * 64 + 16 * tt + 4 * fq);
; #pragma unroll
;                 for (int vt = 0; vt < 3; ++vt)
; #pragma unroll
;                     for (int r = 0; r < 4; ++r) nacc[vt][r] += part[(16 * tt + 4 * fq + r) * PRS + 16 * vt + fr];
; #pragma unroll
;                 for (int r = 0; r < 4; ++r) {
;                     const float den = __shfl(nacc[2][r], lane & 48);
;                     const float inv = __builtin_amdgcn_rcpf(fmaxf(fabsf(den), __expf(-(bc4[r] + fmaxf(m_prev, pm4[r])))));
;                     LAS bf16_t* hrow = (LAS bf16_t*)(shm + HST + (16 * tt + 4 * fq + r) * 80);
;                     hrow[fr] = f2bf(nacc[0][r] * inv);
;                     hrow[16 + fr] = f2bf(nacc[1][r] * inv);
;                 }
;                 asm volatile("s_waitcnt lgkmcnt(0)" ::: "memory");
;                 {
;                     const int rw = 16 * tt + (lane >> 2), pc = lane & 3;
;                     const u32x4 hv = *(const LAS u32x4*)(shm + HST + rw * 80 + pc * 16);
;                     *(uint4*)(hc + cb + (size_t)rw * DM + vs * 32 + pc * 8) = make_uint4(hv[0], hv[1], hv[2], hv[3]);
;                 }
.LBB0_1519:
	s_waitcnt lgkmcnt(0)
	s_barrier
	s_and_b64 vcc, exec, s[26:27]
	s_cbranch_vccnz .LBB0_1521
	ds_read_b128 v[10:13], v228
	ds_read2_b32 v[0:1], v219 offset1:16
	ds_read2_b32 v[4:5], v211 offset1:16
	ds_read2_b32 v[18:19], v211 offset0:32 offset1:52
	ds_read2_b32 v[20:21], v211 offset0:104 offset1:120
	ds_read_b32 v24, v219 offset:128
	v_add_u32_e32 v2, 0x1f500, v2
	s_waitcnt lgkmcnt(4)
	v_add_f32_e32 v22, v118, v0
	v_add_f32_e32 v23, v114, v1
	ds_read2_b32 v[0:1], v211 offset0:68 offset1:84
	ds_read_b128 v[14:17], v2
	ds_read_b32 v2, v211 offset:544
	v_and_or_b32 v25, v214, 64, v179
	v_max_f32_e32 v10, v10, v10
	s_waitcnt lgkmcnt(3)
	v_add_f32_e32 v24, v122, v24
	v_lshlrev_b32_e32 v25, 2, v25
	v_max_f32_e32 v10, v227, v10
	v_mov_b32_dpp v24, v24 row_newbcast:0 row_mask:0xf bank_mask:0xf
	s_waitcnt lgkmcnt(1)
	v_add_f32_e32 v10, v14, v10
	v_mul_f32_e32 v10, 0xbfb8aa3b, v10
	v_exp_f32_e32 v10, v10
	v_add_f32_e32 v14, v117, v21
	s_waitcnt lgkmcnt(0)
	v_max_f32_e64 v21, |v24|, |v24|
	v_max_f32_e32 v11, v11, v11
	v_max_f32_e32 v10, v21, v10
	v_rcp_f32_e32 v10, v10
	v_add_f32_e32 v18, v123, v18
	v_max_f32_e32 v11, v227, v11
	s_nop 0
	v_mov_b32_dpp v18, v18 row_newbcast:0 row_mask:0xf bank_mask:0xf
	v_add_f32_e32 v11, v15, v11
	v_mul_f32_e32 v11, 0xbfb8aa3b, v11
	v_exp_f32_e32 v11, v11
	v_mul_f32_e32 v21, v22, v10
	v_cvt_pk_bf16_f32 v15, v21, s0
	ds_write_b16 v212, v15
	s_waitcnt lgkmcnt(1)
	v_max_f32_e64 v15, |v18|, |v18|
	v_max_f32_e32 v11, v15, v11
	v_rcp_f32_e32 v11, v11
	v_mul_f32_e32 v10, v23, v10
	v_add_f32_e32 v4, v119, v4
	v_cvt_pk_bf16_f32 v10, v10, s0
	ds_write_b16 v212, v10 offset:32
	v_mul_f32_e32 v4, v4, v11
	v_max_f32_e32 v10, v12, v12
	v_add_f32_e32 v5, v115, v5
	v_add_f32_e32 v1, v124, v1
	v_max_f32_e32 v10, v227, v10
	v_cvt_pk_bf16_f32 v4, v4, s0
	v_mov_b32_dpp v1, v1 row_newbcast:0 row_mask:0xf bank_mask:0xf
	v_add_f32_e32 v10, v16, v10
	ds_write_b16 v212, v4 offset:80
	v_mul_f32_e32 v4, v5, v11
	v_max_f32_e32 v5, v13, v13
	v_add_f32_e32 v2, v125, v2
	v_mul_f32_e32 v10, 0xbfb8aa3b, v10
	v_max_f32_e32 v5, v227, v5
	v_exp_f32_e32 v10, v10
	v_mov_b32_dpp v2, v2 row_newbcast:0 row_mask:0xf bank_mask:0xf
	v_add_f32_e32 v5, v17, v5
	v_mul_f32_e32 v5, 0xbfb8aa3b, v5
	v_exp_f32_e32 v5, v5
	s_nop 0
	v_max_f32_e64 v1, |v1|, |v1|
	v_max_f32_e32 v1, v1, v10
	v_rcp_f32_e32 v1, v1
	s_nop 0
	v_max_f32_e64 v2, |v2|, |v2|
	v_max_f32_e32 v2, v2, v5
	v_rcp_f32_e32 v2, v2
	v_add_f32_e32 v0, v116, v0
	v_mul_f32_e32 v0, v0, v1
	v_add_f32_e32 v20, v121, v20
	v_cvt_pk_bf16_f32 v0, v0, s0
	ds_write_b16 v212, v0 offset:192
	v_mul_f32_e32 v0, v20, v2
	v_add_f32_e32 v19, v120, v19
	v_cvt_pk_bf16_f32 v4, v4, s0
	v_cvt_pk_bf16_f32 v0, v0, s0
	ds_write_b16 v212, v4 offset:112
	v_mul_f32_e32 v4, v19, v1
	ds_write_b16 v212, v0 offset:240
	v_mul_f32_e32 v0, v14, v2
	v_cvt_pk_bf16_f32 v4, v4, s0
	v_cvt_pk_bf16_f32 v0, v0, s0
	ds_write_b16 v212, v4 offset:160
	ds_write_b16 v212, v0 offset:272
	s_waitcnt lgkmcnt(0)
	ds_read_b128 v[10:13], v213
	v_lshl_add_u64 v[0:1], v[172:173], 0, s[64:65]
	v_add_co_u32_e32 v0, vcc, 0x4024000, v0
	s_nop 1
	v_addc_co_u32_e32 v1, vcc, 0, v1, vcc
	s_waitcnt lgkmcnt(0)
	global_store_dwordx4 v[0:1], v[10:13], off
